# priority flips plus DA row sums of P via four 16x16x32 MFMAs against a 0/1 indicator operand instead of 32 v_add per tile
# baseline (speedup 1.0000x reference)
.LBB0_598:
	v_add_f32_e32 v184, v18, v19
	v_lshlrev_b32_e32 v18, 1, v50
	v_and_b32_e32 v18, 32, v18
	v_and_or_b32 v18, v51, s66, v18
	v_and_b32_e32 v19, 0x100, v52
	v_fmac_f32_e32 v184, 0, v56
	v_or3_b32 v187, v18, v19, v53
	s_add_i32 s35, 0, 0xc000
	v_cmp_gt_u32_e64 s[4:5], 32, v50
	v_lshl_add_u32 v186, v54, 2, s18
	v_lshlrev_b32_e32 v185, 4, v55
	v_mov_b64_e32 v[32:33], v[16:17]
	v_mov_b64_e32 v[48:49], v[16:17]
	v_mov_b64_e32 v[64:65], v[16:17]
	s_mov_b32 s96, 1
	v_add_u32_e32 v193, s35, v187
	s_lshl_b32 s97, s12, 8
	s_mov_b32 s12, 0x8000
	s_movk_i32 s74, 0x4000
	s_mov_b32 s0, 0
	v_mov_b64_e32 v[30:31], v[14:15]
	v_mov_b64_e32 v[28:29], v[12:13]
	v_mov_b64_e32 v[26:27], v[10:11]
	v_mov_b64_e32 v[24:25], v[8:9]
	v_mov_b64_e32 v[22:23], v[6:7]
	v_mov_b64_e32 v[20:21], v[4:5]
	v_mov_b64_e32 v[18:19], v[2:3]
	v_mov_b64_e32 v[46:47], v[14:15]
	v_mov_b64_e32 v[44:45], v[12:13]
	v_mov_b64_e32 v[42:43], v[10:11]
	v_mov_b64_e32 v[40:41], v[8:9]
	v_mov_b64_e32 v[38:39], v[6:7]
	v_mov_b64_e32 v[36:37], v[4:5]
	v_mov_b64_e32 v[34:35], v[2:3]
	v_mov_b64_e32 v[62:63], v[14:15]
	v_mov_b64_e32 v[60:61], v[12:13]
	v_mov_b64_e32 v[58:59], v[10:11]
	v_mov_b64_e32 v[56:57], v[8:9]
	v_mov_b64_e32 v[54:55], v[6:7]
	v_mov_b64_e32 v[52:53], v[4:5]
	v_mov_b64_e32 v[50:51], v[2:3]
	v_mbcnt_lo_u32_b32 v242, -1, 0
	v_mbcnt_hi_u32_b32 v242, -1, v242
	v_and_b32_e32 v243, 7, v242
	v_lshrrev_b32_e32 v252, 4, v242
	v_lshrrev_b32_e32 v244, 3, v242
	v_xor_b32_e32 v244, v244, v252
	v_and_b32_e32 v244, 1, v244
	v_cmp_eq_u32_e64 s[100:101], 0, v244
	v_mov_b32_e32 v245, 0x3f803f80
	s_nop 1
	v_cndmask_b32_e64 v248, 0, v245, s[100:101]
	v_mov_b32_e32 v249, v248
	v_mov_b32_e32 v250, v248
	v_mov_b32_e32 v251, v248
	v_lshlrev_b32_e32 v252, 4, v252
	v_and_b32_e32 v244, 8, v242
	v_lshl_add_u32 v252, v244, 3, v252
	v_mov_b32_e32 v244, 0
	v_mov_b32_e32 v245, 0
	v_mov_b32_e32 v246, 0
	v_mov_b32_e32 v247, 0
	s_barrier

.LBB0_607:
	s_and_saveexec_b64 s[0:1], s[4:5]
	ds_write_b32 v186, v194 offset:128
	s_or_b64 exec, exec, s[0:1]
	s_waitcnt lgkmcnt(0)
	v_add_u32_e32 v142, s18, v185
	ds_read_b128 v[130:133], v142 offset:224
	ds_read_b128 v[134:137], v142 offset:192
	ds_read_b128 v[138:141], v142 offset:160
	ds_read_b128 v[142:145], v142 offset:128
	s_waitcnt lgkmcnt(0)
	v_pk_mul_f32 v[62:63], v[62:63], v[130:131]
	v_pk_mul_f32 v[58:59], v[58:59], v[134:135]
	v_pk_mul_f32 v[54:55], v[54:55], v[138:139]
	v_pk_mul_f32 v[64:65], v[64:65], v[132:133]
	v_pk_mul_f32 v[60:61], v[60:61], v[136:137]
	v_pk_mul_f32 v[56:57], v[56:57], v[140:141]
	v_pk_mul_f32 v[52:53], v[52:53], v[144:145]
	v_pk_mul_f32 v[50:51], v[50:51], v[142:143]
	v_pk_mul_f32 v[46:47], v[130:131], v[46:47]
	v_pk_mul_f32 v[42:43], v[134:135], v[42:43]
	v_pk_mul_f32 v[38:39], v[138:139], v[38:39]
	v_pk_mul_f32 v[48:49], v[132:133], v[48:49]
	v_pk_mul_f32 v[44:45], v[136:137], v[44:45]
	v_pk_mul_f32 v[40:41], v[140:141], v[40:41]
	v_pk_mul_f32 v[36:37], v[144:145], v[36:37]
	v_pk_mul_f32 v[34:35], v[142:143], v[34:35]
	v_pk_mul_f32 v[30:31], v[130:131], v[30:31]
	v_pk_mul_f32 v[26:27], v[134:135], v[26:27]
	v_pk_mul_f32 v[22:23], v[138:139], v[22:23]
	v_pk_mul_f32 v[32:33], v[132:133], v[32:33]
	v_pk_mul_f32 v[28:29], v[136:137], v[28:29]
	v_pk_mul_f32 v[24:25], v[140:141], v[24:25]
	v_pk_mul_f32 v[20:21], v[144:145], v[20:21]
	v_pk_mul_f32 v[18:19], v[142:143], v[18:19]
	v_pk_mul_f32 v[14:15], v[130:131], v[14:15]
	v_pk_mul_f32 v[10:11], v[134:135], v[10:11]
	v_pk_mul_f32 v[6:7], v[138:139], v[6:7]
	v_pk_mul_f32 v[16:17], v[132:133], v[16:17]
	v_pk_mul_f32 v[12:13], v[136:137], v[12:13]
	v_pk_mul_f32 v[8:9], v[140:141], v[8:9]
	v_pk_mul_f32 v[4:5], v[144:145], v[4:5]
	v_pk_mul_f32 v[2:3], v[142:143], v[2:3]
	v_add_u32_e32 v242, s18, v252
	ds_read_b128 v[142:145], v242 offset:128
	s_waitcnt lgkmcnt(0)
	v_mul_f32_e32 v244, v244, v142
	v_mul_f32_e32 v245, v245, v143
	v_mul_f32_e32 v246, v246, v144
	v_mul_f32_e32 v247, v247, v145
.LBB0_610:
	v_exp_f32_e32 v98, v98
	v_exp_f32_e32 v99, v99
	v_exp_f32_e32 v100, v100
	v_exp_f32_e32 v101, v101
	v_exp_f32_e32 v102, v102
	v_exp_f32_e32 v103, v103
	v_exp_f32_e32 v104, v104
	v_exp_f32_e32 v105, v105
	v_exp_f32_e32 v106, v106
	v_exp_f32_e32 v107, v107
	v_exp_f32_e32 v108, v108
	v_exp_f32_e32 v109, v109
	v_exp_f32_e32 v110, v110
	v_exp_f32_e32 v111, v111
	v_exp_f32_e32 v112, v112
	v_exp_f32_e32 v113, v113
	v_exp_f32_e32 v82, v82
	v_exp_f32_e32 v83, v83
	v_exp_f32_e32 v84, v84
	v_exp_f32_e32 v85, v85
	v_exp_f32_e32 v86, v86
	v_exp_f32_e32 v87, v87
	v_exp_f32_e32 v88, v88
	v_exp_f32_e32 v89, v89
	v_exp_f32_e32 v90, v90
	v_exp_f32_e32 v91, v91
	v_exp_f32_e32 v92, v92
	v_exp_f32_e32 v93, v93
	v_exp_f32_e32 v94, v94
	v_exp_f32_e32 v95, v95
	v_exp_f32_e32 v96, v96
	v_exp_f32_e32 v97, v97
	s_and_b64 vcc, exec, s[2:3]
	v_cvt_pk_bf16_f32 v142, v98, v99
	v_cvt_pk_bf16_f32 v143, v100, v101
	v_cvt_pk_bf16_f32 v144, v102, v103
	v_cvt_pk_bf16_f32 v145, v104, v105
	v_cvt_pk_bf16_f32 v138, v106, v107
	v_cvt_pk_bf16_f32 v139, v108, v109
	v_cvt_pk_bf16_f32 v140, v110, v111
	v_cvt_pk_bf16_f32 v141, v112, v113
	v_cvt_pk_bf16_f32 v134, v82, v83
	v_cvt_pk_bf16_f32 v135, v84, v85
	v_cvt_pk_bf16_f32 v136, v86, v87
	v_cvt_pk_bf16_f32 v137, v88, v89
	v_cvt_pk_bf16_f32 v130, v90, v91
	v_cvt_pk_bf16_f32 v131, v92, v93
	v_cvt_pk_bf16_f32 v132, v94, v95
	v_cvt_pk_bf16_f32 v133, v96, v97
	v_mfma_f32_16x16x32_bf16 v[244:247], v[142:145], v[248:251], v[244:247]
	v_mfma_f32_16x16x32_bf16 v[244:247], v[138:141], v[248:251], v[244:247]
	v_mfma_f32_16x16x32_bf16 v[244:247], v[134:137], v[248:251], v[244:247]
	v_mfma_f32_16x16x32_bf16 v[244:247], v[130:133], v[248:251], v[244:247]
	s_cbranch_vccnz .LBB0_612
	s_waitcnt vmcnt(1)

.LBB0_620:
	s_and_saveexec_b64 s[62:63], s[4:5]
	ds_write_b32 v186, v197 offset:128
	s_or_b64 exec, exec, s[62:63]
	s_waitcnt lgkmcnt(0)
	v_add_u32_e32 v142, s18, v185
	ds_read_b128 v[130:133], v142 offset:224
	ds_read_b128 v[134:137], v142 offset:192
	ds_read_b128 v[138:141], v142 offset:160
	ds_read_b128 v[142:145], v142 offset:128
	s_waitcnt lgkmcnt(0)
	v_pk_mul_f32 v[62:63], v[62:63], v[130:131]
	v_pk_mul_f32 v[58:59], v[58:59], v[134:135]
	v_pk_mul_f32 v[54:55], v[54:55], v[138:139]
	v_pk_mul_f32 v[64:65], v[64:65], v[132:133]
	v_pk_mul_f32 v[60:61], v[60:61], v[136:137]
	v_pk_mul_f32 v[56:57], v[56:57], v[140:141]
	v_pk_mul_f32 v[52:53], v[52:53], v[144:145]
	v_pk_mul_f32 v[50:51], v[50:51], v[142:143]
	v_pk_mul_f32 v[46:47], v[130:131], v[46:47]
	v_pk_mul_f32 v[42:43], v[134:135], v[42:43]
	v_pk_mul_f32 v[38:39], v[138:139], v[38:39]
	v_pk_mul_f32 v[48:49], v[132:133], v[48:49]
	v_pk_mul_f32 v[44:45], v[136:137], v[44:45]
	v_pk_mul_f32 v[40:41], v[140:141], v[40:41]
	v_pk_mul_f32 v[36:37], v[144:145], v[36:37]
	v_pk_mul_f32 v[34:35], v[142:143], v[34:35]
	v_pk_mul_f32 v[30:31], v[130:131], v[30:31]
	v_pk_mul_f32 v[26:27], v[134:135], v[26:27]
	v_pk_mul_f32 v[22:23], v[138:139], v[22:23]
	v_pk_mul_f32 v[32:33], v[132:133], v[32:33]
	v_pk_mul_f32 v[28:29], v[136:137], v[28:29]
	v_pk_mul_f32 v[24:25], v[140:141], v[24:25]
	v_pk_mul_f32 v[20:21], v[144:145], v[20:21]
	v_pk_mul_f32 v[18:19], v[142:143], v[18:19]
	v_pk_mul_f32 v[14:15], v[130:131], v[14:15]
	v_pk_mul_f32 v[10:11], v[134:135], v[10:11]
	v_pk_mul_f32 v[6:7], v[138:139], v[6:7]
	v_pk_mul_f32 v[16:17], v[132:133], v[16:17]
	v_pk_mul_f32 v[12:13], v[136:137], v[12:13]
	v_pk_mul_f32 v[8:9], v[140:141], v[8:9]
	v_pk_mul_f32 v[4:5], v[144:145], v[4:5]
	v_pk_mul_f32 v[2:3], v[142:143], v[2:3]
	v_add_u32_e32 v242, s18, v252
	ds_read_b128 v[142:145], v242 offset:128
	s_waitcnt lgkmcnt(0)
	v_mul_f32_e32 v244, v244, v142
	v_mul_f32_e32 v245, v245, v143
	v_mul_f32_e32 v246, v246, v144
	v_mul_f32_e32 v247, v247, v145
.LBB0_623:
	v_exp_f32_e32 v98, v98
	v_exp_f32_e32 v99, v99
	v_exp_f32_e32 v100, v100
	v_exp_f32_e32 v101, v101
	v_exp_f32_e32 v102, v102
	v_exp_f32_e32 v130, v82
	v_exp_f32_e32 v103, v103
	v_exp_f32_e32 v104, v104
	v_exp_f32_e32 v105, v105
	v_exp_f32_e32 v106, v106
	v_exp_f32_e32 v107, v107
	v_exp_f32_e32 v108, v108
	v_exp_f32_e32 v109, v109
	v_exp_f32_e32 v110, v110
	v_exp_f32_e32 v111, v111
	v_exp_f32_e32 v112, v112
	v_exp_f32_e32 v113, v113
	v_exp_f32_e32 v131, v83
	v_exp_f32_e32 v84, v84
	v_exp_f32_e32 v85, v85
	v_exp_f32_e32 v86, v86
	v_exp_f32_e32 v87, v87
	v_exp_f32_e32 v88, v88
	v_exp_f32_e32 v89, v89
	v_exp_f32_e32 v90, v90
	v_exp_f32_e32 v91, v91
	v_exp_f32_e32 v92, v92
	v_exp_f32_e32 v93, v93
	v_exp_f32_e32 v94, v94
	v_exp_f32_e32 v95, v95
	v_exp_f32_e32 v96, v96
	v_exp_f32_e32 v97, v97
	s_and_b64 vcc, exec, s[2:3]
	v_cvt_pk_bf16_f32 v142, v98, v99
	v_cvt_pk_bf16_f32 v143, v100, v101
	v_cvt_pk_bf16_f32 v144, v102, v103
	v_cvt_pk_bf16_f32 v145, v104, v105
	v_cvt_pk_bf16_f32 v138, v106, v107
	v_cvt_pk_bf16_f32 v139, v108, v109
	v_cvt_pk_bf16_f32 v140, v110, v111
	v_cvt_pk_bf16_f32 v141, v112, v113
	v_cvt_pk_bf16_f32 v134, v130, v131
	v_cvt_pk_bf16_f32 v135, v84, v85
	v_cvt_pk_bf16_f32 v136, v86, v87
	v_cvt_pk_bf16_f32 v137, v88, v89
	v_cvt_pk_bf16_f32 v130, v90, v91
	v_cvt_pk_bf16_f32 v131, v92, v93
	v_cvt_pk_bf16_f32 v132, v94, v95
	v_cvt_pk_bf16_f32 v133, v96, v97
	v_mfma_f32_16x16x32_bf16 v[244:247], v[142:145], v[248:251], v[244:247]
	v_mfma_f32_16x16x32_bf16 v[244:247], v[138:141], v[248:251], v[244:247]
	v_mfma_f32_16x16x32_bf16 v[244:247], v[134:137], v[248:251], v[244:247]
	v_mfma_f32_16x16x32_bf16 v[244:247], v[130:133], v[248:251], v[244:247]
	s_cbranch_vccnz .LBB0_625
	s_waitcnt vmcnt(1)
.LBB0_625:
	v_mul_f32_e32 v84, v184, v194
	v_mul_f32_e32 v184, v84, v197
	s_add_i32 s96, s96, 2
	s_and_b64 vcc, exec, s[0:1]
	s_barrier
	s_cbranch_vccnz .LBB0_629
	s_mov_b32 s0, s12
	s_mov_b32 s12, s75
	s_branch .LBB0_599

.LBB0_633:
	s_and_saveexec_b64 s[0:1], s[4:5]
	ds_write_b32 v186, v114 offset:128
	s_or_b64 exec, exec, s[0:1]
	s_waitcnt lgkmcnt(0)
	v_add_u32_e32 v110, s18, v185
	ds_read_b128 v[98:101], v110 offset:224
	ds_read_b128 v[102:105], v110 offset:192
	ds_read_b128 v[106:109], v110 offset:160
	ds_read_b128 v[110:113], v110 offset:128
	s_waitcnt lgkmcnt(0)
	v_pk_mul_f32 v[62:63], v[62:63], v[98:99]
	v_pk_mul_f32 v[58:59], v[58:59], v[102:103]
	v_pk_mul_f32 v[54:55], v[54:55], v[106:107]
	v_pk_mul_f32 v[64:65], v[64:65], v[100:101]
	v_pk_mul_f32 v[60:61], v[60:61], v[104:105]
	v_pk_mul_f32 v[56:57], v[56:57], v[108:109]
	v_pk_mul_f32 v[52:53], v[52:53], v[112:113]
	v_pk_mul_f32 v[50:51], v[50:51], v[110:111]
	v_pk_mul_f32 v[46:47], v[98:99], v[46:47]
	v_pk_mul_f32 v[42:43], v[102:103], v[42:43]
	v_pk_mul_f32 v[38:39], v[106:107], v[38:39]
	v_pk_mul_f32 v[48:49], v[100:101], v[48:49]
	v_pk_mul_f32 v[44:45], v[104:105], v[44:45]
	v_pk_mul_f32 v[40:41], v[108:109], v[40:41]
	v_pk_mul_f32 v[36:37], v[112:113], v[36:37]
	v_pk_mul_f32 v[34:35], v[110:111], v[34:35]
	v_pk_mul_f32 v[30:31], v[98:99], v[30:31]
	v_pk_mul_f32 v[26:27], v[102:103], v[26:27]
	v_pk_mul_f32 v[22:23], v[106:107], v[22:23]
	v_pk_mul_f32 v[32:33], v[100:101], v[32:33]
	v_pk_mul_f32 v[28:29], v[104:105], v[28:29]
	v_pk_mul_f32 v[24:25], v[108:109], v[24:25]
	v_pk_mul_f32 v[20:21], v[112:113], v[20:21]
	v_pk_mul_f32 v[18:19], v[110:111], v[18:19]
	v_pk_mul_f32 v[14:15], v[98:99], v[14:15]
	v_pk_mul_f32 v[10:11], v[102:103], v[10:11]
	v_pk_mul_f32 v[6:7], v[106:107], v[6:7]
	v_pk_mul_f32 v[16:17], v[100:101], v[16:17]
	v_pk_mul_f32 v[12:13], v[104:105], v[12:13]
	v_pk_mul_f32 v[8:9], v[108:109], v[8:9]
	v_pk_mul_f32 v[4:5], v[112:113], v[4:5]
	v_pk_mul_f32 v[2:3], v[110:111], v[2:3]
	v_add_u32_e32 v242, s18, v252
	ds_read_b128 v[110:113], v242 offset:128
	s_waitcnt lgkmcnt(0)
	v_mul_f32_e32 v244, v244, v110
	v_mul_f32_e32 v245, v245, v111
	v_mul_f32_e32 v246, v246, v112
	v_mul_f32_e32 v247, v247, v113

.LBB0_638:
	s_setprio 0
	s_and_saveexec_b64 s[0:1], s[4:5]
	v_add_f32_e32 v66, v66, v67
	v_fmac_f32_e32 v66, v184, v114
	ds_write_b32 v186, v66
	s_or_b64 exec, exec, s[0:1]
	v_cmp_eq_u32_e64 s[100:101], 0, v243
	s_nop 3
	s_and_saveexec_b64 s[98:99], s[100:101]
	v_add_u32_e32 v242, s18, v252
	ds_add_f32 v242, v244
	ds_add_f32 v242, v245 offset:4
	ds_add_f32 v242, v246 offset:8
	ds_add_f32 v242, v247 offset:12
	s_or_b64 exec, exec, s[98:99]
	s_waitcnt lgkmcnt(0)
	v_add_u32_e32 v78, s18, v185
	ds_read_b128 v[66:69], v78
	ds_read_b128 v[70:73], v78 offset:32
	s_andn2_b64 vcc, exec, s[54:55]
	s_mov_b64 s[0:1], -1
	s_waitcnt lgkmcnt(0)
	v_rcp_f32_e32 v74, v66
	v_rcp_f32_e32 v75, v67
	v_rcp_f32_e32 v76, v68
	v_rcp_f32_e32 v77, v69
	v_pk_mul_f32 v[66:67], v[74:75], v[50:51]
	v_pk_mul_f32 v[50:51], v[74:75], v[34:35]
	v_pk_mul_f32 v[34:35], v[74:75], v[18:19]
	v_pk_mul_f32 v[68:69], v[76:77], v[52:53]
	v_rcp_f32_e32 v18, v70
	v_rcp_f32_e32 v19, v71
	v_pk_mul_f32 v[52:53], v[76:77], v[36:37]
	v_pk_mul_f32 v[36:37], v[76:77], v[20:21]
	v_rcp_f32_e32 v20, v72
	v_rcp_f32_e32 v21, v73
	ds_read_b128 v[70:73], v78 offset:64
	v_pk_mul_f32 v[2:3], v[74:75], v[2:3]
	v_pk_mul_f32 v[4:5], v[76:77], v[4:5]
	ds_read_b128 v[74:77], v78 offset:96
	v_pk_mul_f32 v[54:55], v[18:19], v[54:55]
	v_pk_mul_f32 v[38:39], v[18:19], v[38:39]
	v_pk_mul_f32 v[22:23], v[18:19], v[22:23]
	v_pk_mul_f32 v[18:19], v[18:19], v[6:7]
	v_pk_mul_f32 v[56:57], v[20:21], v[56:57]
	s_waitcnt lgkmcnt(0)
	v_rcp_f32_e32 v6, v70
	v_rcp_f32_e32 v7, v71
	v_pk_mul_f32 v[40:41], v[20:21], v[40:41]
	v_pk_mul_f32 v[24:25], v[20:21], v[24:25]
	v_pk_mul_f32 v[20:21], v[20:21], v[8:9]
	v_rcp_f32_e32 v8, v72
	v_rcp_f32_e32 v9, v73
	v_pk_mul_f32 v[58:59], v[6:7], v[58:59]
	v_pk_mul_f32 v[42:43], v[6:7], v[42:43]
	v_pk_mul_f32 v[26:27], v[6:7], v[26:27]
	v_pk_mul_f32 v[10:11], v[6:7], v[10:11]
	v_pk_mul_f32 v[60:61], v[8:9], v[60:61]
	v_rcp_f32_e32 v6, v74
	v_rcp_f32_e32 v7, v75
	v_pk_mul_f32 v[44:45], v[8:9], v[44:45]
	v_pk_mul_f32 v[28:29], v[8:9], v[28:29]
	v_pk_mul_f32 v[12:13], v[8:9], v[12:13]
	v_rcp_f32_e32 v8, v76
	v_rcp_f32_e32 v9, v77
	s_waitcnt vmcnt(0)
	v_pk_mul_f32 v[62:63], v[6:7], v[62:63]
	v_pk_mul_f32 v[46:47], v[6:7], v[46:47]
	v_pk_mul_f32 v[30:31], v[6:7], v[30:31]
	v_pk_mul_f32 v[6:7], v[6:7], v[14:15]
	v_pk_mul_f32 v[64:65], v[8:9], v[64:65]
	v_pk_mul_f32 v[48:49], v[8:9], v[48:49]
	v_pk_mul_f32 v[32:33], v[8:9], v[32:33]
	v_pk_mul_f32 v[8:9], v[8:9], v[16:17]
	s_waitcnt vmcnt(0)
	s_barrier
	s_cbranch_vccnz .LBB0_575
	v_mov_b64_e32 v[14:15], v[154:155]
	flat_store_dwordx4 v[14:15], v[66:69]
	flat_store_dwordx4 v[14:15], v[54:57] offset:1024
	flat_store_dwordx4 v[14:15], v[58:61] offset:2048
	flat_store_dwordx4 v[14:15], v[62:65] offset:3072
	v_add_co_u32_e32 v16, vcc, 0x1000, v14
	s_mov_b64 s[0:1], 0
	s_nop 0
	v_addc_co_u32_e32 v17, vcc, 0, v15, vcc
	flat_store_dwordx4 v[16:17], v[50:53]
	flat_store_dwordx4 v[16:17], v[38:41] offset:1024
	flat_store_dwordx4 v[16:17], v[42:45] offset:2048
	flat_store_dwordx4 v[16:17], v[46:49] offset:3072
	v_add_co_u32_e32 v16, vcc, s78, v14
	s_nop 1
	v_addc_co_u32_e32 v17, vcc, 0, v15, vcc
	v_add_co_u32_e32 v14, vcc, 0x3000, v14
	flat_store_dwordx4 v[16:17], v[34:37]
	flat_store_dwordx4 v[16:17], v[22:25] offset:1024
	flat_store_dwordx4 v[16:17], v[26:29] offset:2048
	flat_store_dwordx4 v[16:17], v[30:33] offset:3072
	v_addc_co_u32_e32 v15, vcc, 0, v15, vcc
	flat_store_dwordx4 v[14:15], v[2:5]
	flat_store_dwordx4 v[14:15], v[18:21] offset:1024
	flat_store_dwordx4 v[14:15], v[10:13] offset:2048
	flat_store_dwordx4 v[14:15], v[6:9] offset:3072
	s_branch .LBB0_575
